# merged-wait version plus the attention K/V double buffer (global loads with counted vmcnt(8) in the static mixer-A and stick-breaking chunk loops)
# baseline (speedup 1.0000x reference)
; __device__ __forceinline__ float xor32_max(float v) { auto rr = __builtin_amdgcn_permlane32_swap(__float_as_uint(v), __float_as_uint(v), false, false); return fmaxf(__uint_as_float(rr[0]), __uint_as_float(rr[1])); }
; __device__ __forceinline__ int crow(int r, int h) { return (r & 3) + 8 * (r >> 2) + 4 * h; }
; template <int MODE>
; __device__ __forceinline__ void soft_compute(SoftState& st, const bf16x8 (&qf)[4], const KV& t, int k0, int kst, int qp, int W, int dilm1, bool lane_ok, bool diag, const WaveCtx& c) {
;     store_v(t.vr, c);
;     VF vf; read_vf(vf, c);
;     f32x16 s = qk_ref(t.kf, qf, st.negm);
;     if (MODE == 0) {
;         const int relb = qp - k0;
;         const bool cls_ok = ((relb & dilm1) == 0);
; #pragma unroll
;         for (int r = 0; r < 16; ++r) {
;             const unsigned rel = (unsigned)(relb - kst * crow(r, c.h));
;             s[r] = (cls_ok && rel <= (unsigned)W) ? s[r] : -1e30f;
;         }
;     } else if (diag) {
; #pragma unroll
;         for (int r = 0; r < 16; ++r) { const int kp = k0 + crow(r, c.h); s[r] = (kp <= qp) ? s[r] : -1e30f; }
;     } else if (__ballot(!lane_ok) != 0ull) {
; #pragma unroll
;         for (int r = 0; r < 16; ++r) s[r] = lane_ok ? s[r] : -1e30f;
;     }
;     float mx = fmaxf(fmaxf(s[0], s[1]), fmaxf(s[2], s[3]));
; #pragma unroll
;     for (int r = 4; r < 16; r += 4) mx = fmaxf(mx, fmaxf(fmaxf(s[r], s[r + 1]), fmaxf(s[r + 2], s[r + 3])));
;     mx = xor32_max(mx);
;     if (__ballot(mx > 8.0f) != 0ull) {
;         const float d = fmaxf(mx, 0.f), scl = __builtin_amdgcn_exp2f(-d);
;         st.l *= scl; st.m += d;
;         const float nm = -st.m;
; #pragma unroll
;         for (int r = 0; r < 16; ++r) { st.o[0][r] *= scl; st.o[1][r] *= scl; s[r] -= d; st.negm[r] = nm; }
.Lgo_429:
	v_mfma_f32_32x32x16_bf16 v[48:63], v[142:145], v[98:101], v[32:47]
	s_add_i32 s0, s25, -2
	s_cmp_lt_i32 s0, s8
	s_cselect_b32 s0, 0, s8
	s_cselect_b32 s1, s20, s21
	s_add_i32 s0, s0, s24
	s_lshl_b32 s0, s0, s22
	v_subrev_u32_e32 v64, s1, v172
	v_mfma_f32_32x32x16_bf16 v[48:63], v[134:137], v[102:105], v[48:63]
	v_add_u32_e32 v202, s0, v64
	v_and_b32_e32 v64, s23, v202
	v_cmp_eq_u32_e32 vcc, 0, v64
	v_sub_u32_e32 v64, v202, v165
	v_cmp_ge_u32_e64 s[0:1], s19, v64
	v_add_u32_e32 v203, v202, v195
	s_and_b64 s[0:1], vcc, s[0:1]
	v_mfma_f32_32x32x16_bf16 v[48:63], v[126:129], v[106:109], v[48:63]
	v_add_u32_e32 v248, v176, v196
	ds_write_b128 v248, v[138:141]
	ds_write_b128 v192, v[130:133]
	ds_write_b128 v193, v[118:121]
	ds_write_b128 v197, v[114:117]
	v_add_u32_e32 v247, s12, v215
	ds_read_b64_tr_b16 v[158:159], v247
	ds_read_b64_tr_b16 v[160:161], v247 offset:1152
	ds_read_b64_tr_b16 v[156:157], v247 offset:1216
	ds_read_b64_tr_b16 v[154:155], v247 offset:64
	ds_read_b64_tr_b16 v[150:151], v247 offset:2304
	ds_read_b64_tr_b16 v[152:153], v247 offset:3456
	ds_read_b64_tr_b16 v[148:149], v247 offset:3520
	ds_read_b64_tr_b16 v[146:147], v247 offset:2368
	v_mfma_f32_32x32x16_bf16 v[48:63], v[122:125], v[110:113], v[48:63]
	s_nop 11
	v_cndmask_b32_e64 v64, v244, v48, s[0:1]
	v_cmp_ge_u32_e64 s[0:1], s19, v203
	s_and_b64 s[0:1], vcc, s[0:1]
	v_sub_u32_e32 v48, v202, v218
	v_cndmask_b32_e64 v249, v244, v49, s[0:1]
	v_cmp_ge_u32_e64 s[0:1], s19, v48
	s_and_b64 s[0:1], vcc, s[0:1]
	v_sub_u32_e32 v48, v202, v219
	v_cndmask_b32_e64 v250, v244, v50, s[0:1]
	v_cmp_ge_u32_e64 s[0:1], s19, v48
	s_and_b64 s[0:1], vcc, s[0:1]
	v_sub_u32_e32 v48, v202, v220
	v_cndmask_b32_e64 v251, v244, v51, s[0:1]
	v_cmp_ge_u32_e64 s[0:1], s19, v48
	s_and_b64 s[0:1], vcc, s[0:1]
	v_sub_u32_e32 v48, v202, v221
	v_cndmask_b32_e64 v252, v244, v52, s[0:1]
	v_cmp_ge_u32_e64 s[0:1], s19, v48
	s_and_b64 s[0:1], vcc, s[0:1]
	v_sub_u32_e32 v48, v202, v222
	v_cndmask_b32_e64 v53, v244, v53, s[0:1]
	v_cmp_ge_u32_e64 s[0:1], s19, v48
	s_and_b64 s[0:1], vcc, s[0:1]
	v_sub_u32_e32 v48, v202, v223
	v_cndmask_b32_e64 v54, v244, v54, s[0:1]
	v_cmp_ge_u32_e64 s[0:1], s19, v48
	s_and_b64 s[0:1], vcc, s[0:1]
	v_sub_u32_e32 v48, v202, v224
	v_cndmask_b32_e64 v55, v244, v55, s[0:1]
	v_cmp_ge_u32_e64 s[0:1], s19, v48
	s_and_b64 s[0:1], vcc, s[0:1]
	v_sub_u32_e32 v48, v202, v225
	v_cndmask_b32_e64 v253, v244, v56, s[0:1]
	v_cmp_ge_u32_e64 s[0:1], s19, v48
	s_and_b64 s[0:1], vcc, s[0:1]
	v_sub_u32_e32 v48, v202, v226
	v_cndmask_b32_e64 v56, v244, v57, s[0:1]
	v_cmp_ge_u32_e64 s[0:1], s19, v48
	s_and_b64 s[0:1], vcc, s[0:1]
	v_sub_u32_e32 v48, v202, v227
	v_cndmask_b32_e64 v57, v244, v58, s[0:1]
	v_cmp_ge_u32_e64 s[0:1], s19, v48
	s_and_b64 s[0:1], vcc, s[0:1]
	v_sub_u32_e32 v49, v202, v228
	v_cndmask_b32_e64 v48, v244, v59, s[0:1]
	v_cmp_ge_u32_e64 s[0:1], s19, v49
	s_and_b64 s[0:1], vcc, s[0:1]
	v_sub_u32_e32 v50, v202, v229
	v_cndmask_b32_e64 v49, v244, v60, s[0:1]
	v_cmp_ge_u32_e64 s[0:1], s19, v50
	s_and_b64 s[0:1], vcc, s[0:1]
	v_sub_u32_e32 v50, v202, v230
	v_cndmask_b32_e64 v51, v244, v61, s[0:1]
	v_cmp_ge_u32_e64 s[0:1], s19, v50
	v_max_f32_e32 v58, v64, v249
	s_and_b64 s[0:1], vcc, s[0:1]
	v_sub_u32_e32 v52, v202, v231
	v_max_f32_e32 v59, v250, v251
	v_cndmask_b32_e64 v50, v244, v62, s[0:1]
	v_cmp_ge_u32_e64 s[0:1], s19, v52
	v_max_f32_e32 v60, v54, v55
	s_and_b64 vcc, vcc, s[0:1]
	v_max3_f32 v60, v252, v53, v60
	v_cndmask_b32_e32 v52, v244, v63, vcc
	v_max3_f32 v58, v58, v59, v60
	v_max_f32_e32 v59, v57, v48
	v_max_f32_e32 v61, v50, v50
	v_max_f32_e32 v60, v61, v52
	v_max3_f32 v59, v253, v56, v59
	v_max3_f32 v60, v49, v51, v60
	v_max3_f32 v58, v58, v59, v60
	v_mov_b32_e32 v59, v58
	s_nop 1
	v_permlane32_swap_b32_e32 v58, v59
	v_max_f32_e32 v59, v59, v59
	v_max_f32_e32 v58, v58, v59
	v_cmp_lt_f32_e32 vcc, s70, v58
	s_cbranch_vccz .LBB0_431
	v_max_f32_e32 v33, 0, v58
	v_exp_f32_e64 v34, -v33
	v_add_f32_e32 v171, v171, v33
	v_xor_b32_e32 v32, 0x80000000, v171
	v_sub_f32_e32 v64, v64, v33
	v_mul_f32_e32 v170, v170, v34
	v_sub_f32_e32 v249, v249, v33
	v_sub_f32_e32 v250, v250, v33
	v_sub_f32_e32 v251, v251, v33
	v_sub_f32_e32 v252, v252, v33
	v_sub_f32_e32 v53, v53, v33
	v_sub_f32_e32 v54, v54, v33
	v_sub_f32_e32 v55, v55, v33
	v_sub_f32_e32 v253, v253, v33
	v_sub_f32_e32 v56, v56, v33
	v_sub_f32_e32 v57, v57, v33
	v_sub_f32_e32 v48, v48, v33
	v_sub_f32_e32 v49, v49, v33
	v_sub_f32_e32 v51, v51, v33
	v_sub_f32_e32 v50, v50, v33
	v_pk_mul_f32 v[30:31], v[30:31], v[34:35] op_sel_hi:[1,0]
	v_pk_mul_f32 v[28:29], v[28:29], v[34:35] op_sel_hi:[1,0]
	v_pk_mul_f32 v[26:27], v[26:27], v[34:35] op_sel_hi:[1,0]
	v_pk_mul_f32 v[24:25], v[24:25], v[34:35] op_sel_hi:[1,0]
	v_pk_mul_f32 v[22:23], v[22:23], v[34:35] op_sel_hi:[1,0]
	v_pk_mul_f32 v[20:21], v[20:21], v[34:35] op_sel_hi:[1,0]
	v_pk_mul_f32 v[18:19], v[18:19], v[34:35] op_sel_hi:[1,0]
	v_pk_mul_f32 v[16:17], v[16:17], v[34:35] op_sel_hi:[1,0]
	v_pk_mul_f32 v[14:15], v[14:15], v[34:35] op_sel_hi:[1,0]
	v_pk_mul_f32 v[12:13], v[12:13], v[34:35] op_sel_hi:[1,0]
	v_pk_mul_f32 v[10:11], v[10:11], v[34:35] op_sel_hi:[1,0]
	v_pk_mul_f32 v[8:9], v[8:9], v[34:35] op_sel_hi:[1,0]
	v_pk_mul_f32 v[6:7], v[6:7], v[34:35] op_sel_hi:[1,0]
	v_pk_mul_f32 v[4:5], v[4:5], v[34:35] op_sel_hi:[1,0]
	v_pk_mul_f32 v[2:3], v[2:3], v[34:35] op_sel_hi:[1,0]
	v_pk_mul_f32 v[0:1], v[0:1], v[34:35] op_sel_hi:[1,0]
	v_sub_f32_e32 v52, v52, v33
	v_mov_b32_e32 v33, v32
	v_mov_b32_e32 v34, v32
	v_mov_b32_e32 v35, v32
	v_mov_b32_e32 v36, v32
	v_mov_b32_e32 v37, v32
	v_mov_b32_e32 v38, v32
	v_mov_b32_e32 v39, v32
	v_mov_b32_e32 v40, v32
	v_mov_b32_e32 v41, v32
	v_mov_b32_e32 v42, v32
	v_mov_b32_e32 v43, v32
	v_mov_b32_e32 v44, v32
	v_mov_b32_e32 v45, v32
	v_mov_b32_e32 v46, v32
	v_mov_b32_e32 v47, v32

; __device__ __forceinline__ float xor32_max(float v) { auto rr = __builtin_amdgcn_permlane32_swap(__float_as_uint(v), __float_as_uint(v), false, false); return fmaxf(__uint_as_float(rr[0]), __uint_as_float(rr[1])); }
; __device__ __forceinline__ int crow(int r, int h) { return (r & 3) + 8 * (r >> 2) + 4 * h; }
; template <int MODE>
; __device__ __forceinline__ void soft_compute(SoftState& st, const bf16x8 (&qf)[4], const KV& t, int k0, int kst, int qp, int W, int dilm1, bool lane_ok, bool diag, const WaveCtx& c) {
;     store_v(t.vr, c);
;     VF vf; read_vf(vf, c);
;     f32x16 s = qk_ref(t.kf, qf, st.negm);
;     if (MODE == 0) {
;         const int relb = qp - k0;
;         const bool cls_ok = ((relb & dilm1) == 0);
; #pragma unroll
;         for (int r = 0; r < 16; ++r) {
;             const unsigned rel = (unsigned)(relb - kst * crow(r, c.h));
;             s[r] = (cls_ok && rel <= (unsigned)W) ? s[r] : -1e30f;
;         }
;     } else if (diag) {
; #pragma unroll
;         for (int r = 0; r < 16; ++r) { const int kp = k0 + crow(r, c.h); s[r] = (kp <= qp) ? s[r] : -1e30f; }
;     } else if (__ballot(!lane_ok) != 0ull) {
; #pragma unroll
;         for (int r = 0; r < 16; ++r) s[r] = lane_ok ? s[r] : -1e30f;
;     }
;     float mx = fmaxf(fmaxf(s[0], s[1]), fmaxf(s[2], s[3]));
; #pragma unroll
;     for (int r = 4; r < 16; r += 4) mx = fmaxf(mx, fmaxf(fmaxf(s[r], s[r + 1]), fmaxf(s[r + 2], s[r + 3])));
;     mx = xor32_max(mx);
;     if (__ballot(mx > 8.0f) != 0ull) {
;         const float d = fmaxf(mx, 0.f), scl = __builtin_amdgcn_exp2f(-d);
;         st.l *= scl; st.m += d;
;         const float nm = -st.m;
; #pragma unroll
;         for (int r = 0; r < 16; ++r) { st.o[0][r] *= scl; st.o[1][r] *= scl; s[r] -= d; st.negm[r] = nm; }
.LBB0_434:
	s_waitcnt vmcnt(0)
.Lgo_434:
	v_mfma_f32_32x32x16_bf16 v[48:63], v[66:69], v[98:101], v[32:47]
	s_cmp_lt_i32 s26, s8
	s_cselect_b32 s0, 0, s8
	s_cselect_b32 s1, s20, s21
	s_add_i32 s0, s0, s24
	s_add_i32 s0, s0, -1
	s_lshl_b32 s0, s0, s22
	v_subrev_u32_e32 v64, s1, v172
	v_mfma_f32_32x32x16_bf16 v[48:63], v[70:73], v[102:105], v[48:63]
	v_add_u32_e32 v202, s0, v64
	v_and_b32_e32 v64, s23, v202
	v_cmp_eq_u32_e32 vcc, 0, v64
	v_sub_u32_e32 v64, v202, v165
	v_cmp_ge_u32_e64 s[0:1], s19, v64
	s_and_b64 s[0:1], vcc, s[0:1]
	ds_write_b128 v248, v[82:85]
	ds_write_b128 v192, v[86:89]
	ds_write_b128 v193, v[90:93]
	ds_write_b128 v197, v[94:97]
	v_mfma_f32_32x32x16_bf16 v[48:63], v[74:77], v[106:109], v[48:63]
	ds_read_b64_tr_b16 v[158:159], v247
	ds_read_b64_tr_b16 v[160:161], v247 offset:1152
	ds_read_b64_tr_b16 v[150:151], v247 offset:2304
	ds_read_b64_tr_b16 v[152:153], v247 offset:3456
	ds_read_b64_tr_b16 v[154:155], v247 offset:64
	ds_read_b64_tr_b16 v[156:157], v247 offset:1216
	ds_read_b64_tr_b16 v[146:147], v247 offset:2368
	ds_read_b64_tr_b16 v[148:149], v247 offset:3520
	v_mfma_f32_32x32x16_bf16 v[48:63], v[78:81], v[110:113], v[48:63]
	s_nop 11
	v_cndmask_b32_e64 v64, v244, v48, s[0:1]
	v_add_u32_e32 v48, v202, v195
	v_cmp_ge_u32_e64 s[0:1], s19, v48
	s_and_b64 s[0:1], vcc, s[0:1]
	v_sub_u32_e32 v48, v202, v218
	v_cndmask_b32_e64 v247, v244, v49, s[0:1]
	v_cmp_ge_u32_e64 s[0:1], s19, v48
	s_and_b64 s[0:1], vcc, s[0:1]
	v_sub_u32_e32 v48, v202, v219
	v_cndmask_b32_e64 v248, v244, v50, s[0:1]
	v_cmp_ge_u32_e64 s[0:1], s19, v48
	s_and_b64 s[0:1], vcc, s[0:1]
	v_sub_u32_e32 v48, v202, v220
	v_cndmask_b32_e64 v249, v244, v51, s[0:1]
	v_cmp_ge_u32_e64 s[0:1], s19, v48
	s_and_b64 s[0:1], vcc, s[0:1]
	v_sub_u32_e32 v48, v202, v221
	v_cndmask_b32_e64 v250, v244, v52, s[0:1]
	v_cmp_ge_u32_e64 s[0:1], s19, v48
	s_and_b64 s[0:1], vcc, s[0:1]
	v_sub_u32_e32 v48, v202, v222
	v_cndmask_b32_e64 v53, v244, v53, s[0:1]
	v_cmp_ge_u32_e64 s[0:1], s19, v48
	s_and_b64 s[0:1], vcc, s[0:1]
	v_sub_u32_e32 v48, v202, v223
	v_cndmask_b32_e64 v54, v244, v54, s[0:1]
	v_cmp_ge_u32_e64 s[0:1], s19, v48
	s_and_b64 s[0:1], vcc, s[0:1]
	v_sub_u32_e32 v48, v202, v224
	v_cndmask_b32_e64 v55, v244, v55, s[0:1]
	v_cmp_ge_u32_e64 s[0:1], s19, v48
	s_and_b64 s[0:1], vcc, s[0:1]
	v_sub_u32_e32 v48, v202, v225
	v_cndmask_b32_e64 v251, v244, v56, s[0:1]
	v_cmp_ge_u32_e64 s[0:1], s19, v48
	s_and_b64 s[0:1], vcc, s[0:1]
	v_sub_u32_e32 v48, v202, v226
	v_cndmask_b32_e64 v56, v244, v57, s[0:1]
	v_cmp_ge_u32_e64 s[0:1], s19, v48
	s_and_b64 s[0:1], vcc, s[0:1]
	v_sub_u32_e32 v48, v202, v227
	v_cndmask_b32_e64 v57, v244, v58, s[0:1]
	v_cmp_ge_u32_e64 s[0:1], s19, v48
	s_and_b64 s[0:1], vcc, s[0:1]
	v_sub_u32_e32 v49, v202, v228
	v_cndmask_b32_e64 v48, v244, v59, s[0:1]
	v_cmp_ge_u32_e64 s[0:1], s19, v49
	s_and_b64 s[0:1], vcc, s[0:1]
	v_sub_u32_e32 v50, v202, v229
	v_cndmask_b32_e64 v49, v244, v60, s[0:1]
	v_cmp_ge_u32_e64 s[0:1], s19, v50
	s_and_b64 s[0:1], vcc, s[0:1]
	v_sub_u32_e32 v50, v202, v230
	v_cndmask_b32_e64 v51, v244, v61, s[0:1]
	v_cmp_ge_u32_e64 s[0:1], s19, v50
	v_max_f32_e32 v58, v64, v247
	s_and_b64 s[0:1], vcc, s[0:1]
	v_sub_u32_e32 v52, v202, v231
	v_max_f32_e32 v59, v248, v249
	v_cndmask_b32_e64 v50, v244, v62, s[0:1]
	v_cmp_ge_u32_e64 s[0:1], s19, v52
	v_max_f32_e32 v60, v54, v55
	s_and_b64 vcc, vcc, s[0:1]
	v_max3_f32 v60, v250, v53, v60
	v_cndmask_b32_e32 v52, v244, v63, vcc
	v_max3_f32 v58, v58, v59, v60
	v_max_f32_e32 v59, v57, v48
	v_max_f32_e32 v61, v50, v50
	v_max_f32_e32 v60, v61, v52
	v_max3_f32 v59, v251, v56, v59
	v_max3_f32 v60, v49, v51, v60
	v_max3_f32 v58, v58, v59, v60
	v_mov_b32_e32 v59, v58
	s_nop 1
	v_permlane32_swap_b32_e32 v58, v59
	v_max_f32_e32 v59, v59, v59
	v_max_f32_e32 v58, v58, v59
	v_cmp_lt_f32_e32 vcc, s70, v58
	s_cbranch_vccz .LBB0_436
	v_max_f32_e32 v33, 0, v58
	v_exp_f32_e64 v34, -v33
	v_add_f32_e32 v171, v171, v33
	v_xor_b32_e32 v32, 0x80000000, v171
	v_sub_f32_e32 v64, v64, v33
	v_mul_f32_e32 v170, v170, v34
	v_sub_f32_e32 v247, v247, v33
	v_sub_f32_e32 v248, v248, v33
	v_sub_f32_e32 v249, v249, v33
	v_sub_f32_e32 v250, v250, v33
	v_sub_f32_e32 v53, v53, v33
	v_sub_f32_e32 v54, v54, v33
	v_sub_f32_e32 v55, v55, v33
	v_sub_f32_e32 v251, v251, v33
	v_sub_f32_e32 v56, v56, v33
	v_sub_f32_e32 v57, v57, v33
	v_sub_f32_e32 v48, v48, v33
	v_sub_f32_e32 v49, v49, v33
	v_sub_f32_e32 v51, v51, v33
	v_sub_f32_e32 v50, v50, v33
	v_pk_mul_f32 v[30:31], v[30:31], v[34:35] op_sel_hi:[1,0]
	v_pk_mul_f32 v[28:29], v[28:29], v[34:35] op_sel_hi:[1,0]
	v_pk_mul_f32 v[26:27], v[26:27], v[34:35] op_sel_hi:[1,0]
	v_pk_mul_f32 v[24:25], v[24:25], v[34:35] op_sel_hi:[1,0]
	v_pk_mul_f32 v[22:23], v[22:23], v[34:35] op_sel_hi:[1,0]
	v_pk_mul_f32 v[20:21], v[20:21], v[34:35] op_sel_hi:[1,0]
	v_pk_mul_f32 v[18:19], v[18:19], v[34:35] op_sel_hi:[1,0]
	v_pk_mul_f32 v[16:17], v[16:17], v[34:35] op_sel_hi:[1,0]
	v_pk_mul_f32 v[14:15], v[14:15], v[34:35] op_sel_hi:[1,0]
	v_pk_mul_f32 v[12:13], v[12:13], v[34:35] op_sel_hi:[1,0]
	v_pk_mul_f32 v[10:11], v[10:11], v[34:35] op_sel_hi:[1,0]
	v_pk_mul_f32 v[8:9], v[8:9], v[34:35] op_sel_hi:[1,0]
	v_pk_mul_f32 v[6:7], v[6:7], v[34:35] op_sel_hi:[1,0]
	v_pk_mul_f32 v[4:5], v[4:5], v[34:35] op_sel_hi:[1,0]
	v_pk_mul_f32 v[2:3], v[2:3], v[34:35] op_sel_hi:[1,0]
	v_pk_mul_f32 v[0:1], v[0:1], v[34:35] op_sel_hi:[1,0]
	v_sub_f32_e32 v52, v52, v33
	v_mov_b32_e32 v33, v32
	v_mov_b32_e32 v34, v32
	v_mov_b32_e32 v35, v32
	v_mov_b32_e32 v36, v32
	v_mov_b32_e32 v37, v32
	v_mov_b32_e32 v38, v32
	v_mov_b32_e32 v39, v32
	v_mov_b32_e32 v40, v32
	v_mov_b32_e32 v41, v32
	v_mov_b32_e32 v42, v32
	v_mov_b32_e32 v43, v32
	v_mov_b32_e32 v44, v32
	v_mov_b32_e32 v45, v32
	v_mov_b32_e32 v46, v32
	v_mov_b32_e32 v47, v32
